# v18 + split-phase grid barrier retc->in-proj(b+1): arrive, run first in-proj tile K-loop, wait before first epilogue (b<3 only)
# speedup vs baseline: 1.0103x; 1.0059x over previous
; #define LAS __attribute__((address_space(3)))
; __device__ __forceinline__ KParams kparams() { unsigned long long a = (unsigned long long)__builtin_amdgcn_kernarg_segment_ptr(); asm volatile("" : "+s"(a)); return (KParams)a; }
; __global__ void __launch_bounds__(512, 2) mega(Params p_unused) {
;     extern __shared__ __attribute__((aligned(16))) unsigned char shm[];
;     LAS unsigned char* lds = (LAS unsigned char*)shm;
;     const unsigned ldsb = (unsigned)(size_t)lds;
;     const int wv = __builtin_amdgcn_readfirstlane((int)(threadIdx.x >> 6));
;     cg::grid_group grid = cg::this_grid();
;     volatile LAS unsigned* xst = (volatile LAS unsigned*)(lds + LDS_BYTES - 16);
;     if (TIDX == 0) { xst[0] = 0u; xst[1] = 0u; }
;     __syncthreads();
;     const XcdBarrier xb = xcd_barrier_post(wv, (unsigned*)(kparams()->ws + WS_BAR), xst);
_Z4mega6Params:
	s_mov_b64 s[56:57], s[0:1]
	s_mov_b32 s101, 0
	v_and_b32_e32 v1, 0x3ff, v0
	s_load_dwordx2 s[54:55], s[56:57], 0x78
	s_load_dword s33, s[56:57], 0x80
	v_readfirstlane_b32 s0, v1
	s_and_b32 s53, s0, 0xffffffc0
	v_mbcnt_lo_u32_b32 v2, -1, 0
	v_mbcnt_hi_u32_b32 v2, -1, v2
	s_add_u32 s8, s56, 0x78
	v_sub_u32_e32 v2, 0, v2
	s_mov_b32 s66, s2
	s_addc_u32 s9, s57, 0
	v_cmp_eq_u32_e32 vcc, s53, v2
	s_and_saveexec_b64 s[0:1], vcc
	s_cbranch_execz .LBB0_2
	s_add_i32 s2, 0, 0x21ff0
	v_mov_b32_e32 v2, 0
	v_mov_b32_e32 v3, s2
	s_add_i32 s2, 0, 0x21ff4
	ds_write_b32 v3, v2
	v_mov_b32_e32 v3, s2
	ds_write_b32 v3, v2

; #define PG8_STAGE(bufoff, gbase, voff) do { _Pragma("unroll") for (int _i = 0; _i < 2; ++_i) \
;         __builtin_amdgcn_global_load_lds((const unsigned*)((const char*)(gbase) + (voff)[_i]), (LAS unsigned*)(lds + (bufoff) + ldsw + _i * 8192), 16, 0, 0); } while (0)
; #define PG8_LDA(dst, b, h) do { _Pragma("unroll") for (int m = 0; m < 4; ++m) _Pragma("unroll") for (int k = 0; k < 2; ++k) dst[m][k] = *(const LAS bf16x8*)(lds + PG8_SA(b, h) + aoff + m * 2048 + k * 1024); } while (0)
; #define PG8_LDB(dst, b, h) do { _Pragma("unroll") for (int n = 0; n < 2; ++n) _Pragma("unroll") for (int k = 0; k < 2; ++k) dst[n][k] = *(const LAS bf16x8*)(lds + PG8_SB(b, h) + boff + n * 2048 + k * 1024); } while (0)
; #define PG8_WAIT_V(n) asm volatile("s_waitcnt vmcnt(" #n ")" ::: "memory")
; #define PG8_WAIT_L(n) asm volatile("s_waitcnt lgkmcnt(" #n ")" ::: "memory")
; #define PG8_BAR __builtin_amdgcn_s_barrier()
; #define PG8_SCHED __builtin_amdgcn_sched_barrier(0)
; template <class Epi, class Sched>
; __device__ __forceinline__ void gemm_phase(const int wv, LAS unsigned char* lds, const Gemm g, const Sched& S, const Epi& E) {
;     ...
;             PG8_LDB(B0, 0, 0); PG8_SCHED; PG8_LDA(At, 0, 0); PG8_STAGE(PG8_SA(1, 1), a1 + hstepA, voffA);
;             PG8_WAIT_L(8); PG8_BAR; PG8_WAIT_L(0); PG8_MMA(0, 0, At, B0); PG8_BAR; PG8_SCHED;
;             PG8_LDB(B1, 0, 1); PG8_STAGE(PG8_SB(0, 0), b2, voffB);
;             PG8_BAR; PG8_WAIT_L(0); PG8_MMA(0, 1, At, B1); PG8_BAR;
;             PG8_LDA(At, 0, 1); PG8_STAGE(PG8_SA(0, 0), a2, voffA);
;             PG8_BAR; PG8_WAIT_L(0); PG8_MMA(1, 0, At, B0); PG8_BAR; PG8_SCHED;
;             PG8_STAGE(PG8_SB(0, 1), b2 + hstepB, voffB);
;             PG8_WAIT_V(6); PG8_BAR; PG8_MMA(1, 1, At, B1); PG8_BAR;
;             PG8_LDB(B0, 1, 0); PG8_SCHED; PG8_LDA(At, 1, 0); PG8_STAGE(PG8_SA(0, 1), a2 + hstepA, voffA);
;             PG8_WAIT_L(8); PG8_BAR; PG8_WAIT_L(0); PG8_MMA(0, 0, At, B0); PG8_BAR; PG8_SCHED;
;             PG8_LDB(B1, 1, 1); PG8_STAGE(PG8_SB(1, 0), b3, voffB);
;             PG8_BAR; PG8_WAIT_L(0); PG8_MMA(0, 1, At, B1); PG8_BAR;
;             PG8_LDA(At, 1, 1); PG8_STAGE(PG8_SA(1, 0), a3, voffA);
;             PG8_BAR; PG8_WAIT_L(0); PG8_MMA(1, 0, At, B0); PG8_BAR; PG8_SCHED;
;             PG8_STAGE(PG8_SB(1, 1), b3 + hstepB, voffB);
;             PG8_WAIT_V(6); PG8_BAR; PG8_MMA(1, 1, At, B1); PG8_BAR;
.LBB0_147:
	s_add_u32 s24, s22, 0xfffc0080
	s_addc_u32 s25, s23, -1
	s_add_i32 s31, 0, 0x10000
	v_add_u32_e32 v150, s31, v152
	ds_read_b128 v[142:145], v150
	ds_read_b128 v[146:149], v150 offset:1024
	ds_read_b128 v[160:163], v150 offset:2048
	ds_read_b128 v[164:167], v150 offset:3072
	s_cmp_eq_u32 s30, 12
	s_cselect_b32 s27, s1, s25
	s_cselect_b32 s26, s3, s24
	s_cselect_b32 s25, s13, s29
	s_cselect_b32 s24, s15, s28
	v_lshl_add_u64 v[150:151], s[22:23], 0, v[138:139]
	s_add_i32 m0, s45, 0xc000
	ds_read_b128 v[168:171], v158
	ds_read_b128 v[172:175], v158 offset:1024
	ds_read_b128 v[180:183], v158 offset:2048
	ds_read_b128 v[192:195], v158 offset:3072
	ds_read_b128 v[196:199], v158 offset:4096
	ds_read_b128 v[200:203], v158 offset:5120
	ds_read_b128 v[204:207], v158 offset:6144
	ds_read_b128 v[208:211], v158 offset:7168
	global_load_lds_dwordx4 v[150:151], off
	s_add_i32 m0, s45, 0xe000
	v_lshl_add_u64 v[150:151], s[22:23], 0, v[140:141]
	global_load_lds_dwordx4 v[150:151], off
	s_waitcnt lgkmcnt(8)
	s_barrier
	s_waitcnt lgkmcnt(0)
	v_mfma_f32_16x16x32_bf16 v[126:129], v[142:145], v[168:171], v[126:129]
	v_mfma_f32_16x16x32_bf16 v[122:125], v[160:163], v[168:171], v[122:125]
	v_mfma_f32_16x16x32_bf16 v[110:113], v[142:145], v[180:183], v[110:113]
	v_mfma_f32_16x16x32_bf16 v[106:109], v[160:163], v[180:183], v[106:109]
	v_mfma_f32_16x16x32_bf16 v[94:97], v[142:145], v[196:199], v[94:97]
	v_mfma_f32_16x16x32_bf16 v[90:93], v[160:163], v[196:199], v[90:93]
	v_mfma_f32_16x16x32_bf16 v[78:81], v[142:145], v[204:207], v[78:81]
	v_mfma_f32_16x16x32_bf16 v[74:77], v[160:163], v[204:207], v[74:77]
	v_mfma_f32_16x16x32_bf16 v[126:129], v[146:149], v[172:175], v[126:129]
	v_mfma_f32_16x16x32_bf16 v[122:125], v[164:167], v[172:175], v[122:125]
	v_mfma_f32_16x16x32_bf16 v[110:113], v[146:149], v[192:195], v[110:113]
	v_mfma_f32_16x16x32_bf16 v[106:109], v[164:167], v[192:195], v[106:109]
	v_mfma_f32_16x16x32_bf16 v[94:97], v[146:149], v[200:203], v[94:97]
	v_mfma_f32_16x16x32_bf16 v[90:93], v[164:167], v[200:203], v[90:93]
	v_mfma_f32_16x16x32_bf16 v[78:81], v[146:149], v[208:211], v[78:81]
	v_mfma_f32_16x16x32_bf16 v[74:77], v[164:167], v[208:211], v[74:77]
	s_barrier
	s_add_i32 s52, 0, 0x14000
	v_add_u32_e32 v150, s52, v152
	s_add_i32 s31, s31, s44
	ds_read_b128 v[212:215], v150
	ds_read_b128 v[216:219], v150 offset:1024
	ds_read_b128 v[220:223], v150 offset:2048
	ds_read_b128 v[224:227], v150 offset:3072
	v_lshl_add_u64 v[150:151], s[24:25], 0, v[132:133]
	s_mov_b32 m0, s31
	v_lshl_add_u64 v[176:177], s[24:25], 0, v[136:137]
	global_load_lds_dwordx4 v[150:151], off
	s_add_i32 m0, s31, 0x2000
	s_nop 0
	global_load_lds_dwordx4 v[176:177], off
	s_barrier
	s_waitcnt lgkmcnt(0)
	v_mfma_f32_16x16x32_bf16 v[118:121], v[212:215], v[168:171], v[118:121]
	v_mfma_f32_16x16x32_bf16 v[114:117], v[220:223], v[168:171], v[114:117]
	v_mfma_f32_16x16x32_bf16 v[102:105], v[212:215], v[180:183], v[102:105]
	v_mfma_f32_16x16x32_bf16 v[98:101], v[220:223], v[180:183], v[98:101]
	v_mfma_f32_16x16x32_bf16 v[86:89], v[212:215], v[196:199], v[86:89]
	v_mfma_f32_16x16x32_bf16 v[82:85], v[220:223], v[196:199], v[82:85]
	v_mfma_f32_16x16x32_bf16 v[70:73], v[212:215], v[204:207], v[70:73]
	v_mfma_f32_16x16x32_bf16 v[66:69], v[220:223], v[204:207], v[66:69]
	v_mfma_f32_16x16x32_bf16 v[118:121], v[216:219], v[172:175], v[118:121]
	v_mfma_f32_16x16x32_bf16 v[114:117], v[224:227], v[172:175], v[114:117]
	v_mfma_f32_16x16x32_bf16 v[102:105], v[216:219], v[192:195], v[102:105]
	v_mfma_f32_16x16x32_bf16 v[98:101], v[224:227], v[192:195], v[98:101]
	v_mfma_f32_16x16x32_bf16 v[86:89], v[216:219], v[200:203], v[86:89]
	v_mfma_f32_16x16x32_bf16 v[82:85], v[224:227], v[200:203], v[82:85]
	v_mfma_f32_16x16x32_bf16 v[70:73], v[216:219], v[208:211], v[70:73]
	v_mfma_f32_16x16x32_bf16 v[66:69], v[224:227], v[208:211], v[66:69]
	s_mov_b32 m0, s45
	v_lshl_add_u64 v[228:229], s[26:27], 0, v[130:131]
	s_barrier
	ds_read_b128 v[168:171], v158 offset:16384
	ds_read_b128 v[172:175], v158 offset:17408
	ds_read_b128 v[180:183], v158 offset:18432
	ds_read_b128 v[192:195], v158 offset:19456
	ds_read_b128 v[196:199], v158 offset:20480
	ds_read_b128 v[200:203], v158 offset:21504
	ds_read_b128 v[204:207], v158 offset:22528
	ds_read_b128 v[208:211], v158 offset:23552
	global_load_lds_dwordx4 v[228:229], off
	s_mov_b32 m0, s46
	v_lshl_add_u64 v[230:231], s[26:27], 0, v[134:135]
	global_load_lds_dwordx4 v[230:231], off
	s_barrier
	s_waitcnt lgkmcnt(0)
	v_mfma_f32_16x16x32_bf16 v[62:65], v[142:145], v[168:171], v[62:65]
	v_mfma_f32_16x16x32_bf16 v[58:61], v[160:163], v[168:171], v[58:61]
	v_mfma_f32_16x16x32_bf16 v[46:49], v[142:145], v[180:183], v[46:49]
	v_mfma_f32_16x16x32_bf16 v[42:45], v[160:163], v[180:183], v[42:45]
	v_mfma_f32_16x16x32_bf16 v[30:33], v[142:145], v[196:199], v[30:33]
	v_mfma_f32_16x16x32_bf16 v[26:29], v[160:163], v[196:199], v[26:29]
	v_mfma_f32_16x16x32_bf16 v[14:17], v[142:145], v[204:207], v[14:17]
	v_mfma_f32_16x16x32_bf16 v[10:13], v[160:163], v[204:207], v[10:13]
	v_mfma_f32_16x16x32_bf16 v[62:65], v[146:149], v[172:175], v[62:65]
	v_mfma_f32_16x16x32_bf16 v[58:61], v[164:167], v[172:175], v[58:61]
	v_mfma_f32_16x16x32_bf16 v[46:49], v[146:149], v[192:195], v[46:49]
	v_mfma_f32_16x16x32_bf16 v[42:45], v[164:167], v[192:195], v[42:45]
	v_mfma_f32_16x16x32_bf16 v[30:33], v[146:149], v[200:203], v[30:33]
	v_mfma_f32_16x16x32_bf16 v[26:29], v[164:167], v[200:203], v[26:29]
	v_mfma_f32_16x16x32_bf16 v[14:17], v[146:149], v[208:211], v[14:17]
	v_mfma_f32_16x16x32_bf16 v[10:13], v[164:167], v[208:211], v[10:13]
	s_barrier
; #define PG8_STAGE(bufoff, gbase, voff) do { _Pragma("unroll") for (int _i = 0; _i < 2; ++_i) \
;         __builtin_amdgcn_global_load_lds((const unsigned*)((const char*)(gbase) + (voff)[_i]), (LAS unsigned*)(lds + (bufoff) + ldsw + _i * 8192), 16, 0, 0); } while (0)
; #define PG8_LDA(dst, b, h) do { _Pragma("unroll") for (int m = 0; m < 4; ++m) _Pragma("unroll") for (int k = 0; k < 2; ++k) dst[m][k] = *(const LAS bf16x8*)(lds + PG8_SA(b, h) + aoff + m * 2048 + k * 1024); } while (0)
; #define PG8_LDB(dst, b, h) do { _Pragma("unroll") for (int n = 0; n < 2; ++n) _Pragma("unroll") for (int k = 0; k < 2; ++k) dst[n][k] = *(const LAS bf16x8*)(lds + PG8_SB(b, h) + boff + n * 2048 + k * 1024); } while (0)
; #define PG8_MMA(ai, bj, At, Bt) do { __builtin_amdgcn_s_setprio(1); _Pragma("unroll") for (int m = 0; m < 4; ++m) _Pragma("unroll") for (int n = 0; n < 2; ++n) _Pragma("unroll") for (int k = 0; k < 2; ++k) \
;         acc[ai][bj][m][n] = __builtin_amdgcn_mfma_f32_16x16x32_bf16(Bt[n][k], At[m][k], acc[ai][bj][m][n], 0, 0, 0); __builtin_amdgcn_s_setprio(0); } while (0)
; #define PG8_WAIT_V(n) asm volatile("s_waitcnt vmcnt(" #n ")" ::: "memory")
; #define PG8_WAIT_L(n) asm volatile("s_waitcnt lgkmcnt(" #n ")" ::: "memory")
; #define PG8_BAR __builtin_amdgcn_s_barrier()
; #define PG8_SCHED __builtin_amdgcn_sched_barrier(0)
; template <class Epi, class Sched>
; __device__ __forceinline__ void gemm_phase(const int wv, LAS unsigned char* lds, const Gemm g, const Sched& S, const Epi& E) {
;     ...
;             PG8_BAR; PG8_WAIT_L(0); PG8_MMA(0, 1, At, B1); PG8_BAR;
;             PG8_LDA(At, 0, 1); PG8_STAGE(PG8_SA(0, 0), a2, voffA);
;             PG8_BAR; PG8_WAIT_L(0); PG8_MMA(1, 0, At, B0); PG8_BAR; PG8_SCHED;
;             PG8_STAGE(PG8_SB(0, 1), b2 + hstepB, voffB);
;             PG8_WAIT_V(6); PG8_BAR; PG8_MMA(1, 1, At, B1); PG8_BAR;
;             PG8_LDB(B0, 1, 0); PG8_SCHED; PG8_LDA(At, 1, 0); PG8_STAGE(PG8_SA(0, 1), a2 + hstepA, voffA);
;             PG8_WAIT_L(8); PG8_BAR; PG8_WAIT_L(0); PG8_MMA(0, 0, At, B0); PG8_BAR; PG8_SCHED;
;             PG8_LDB(B1, 1, 1); PG8_STAGE(PG8_SB(1, 0), b3, voffB);
;             PG8_BAR; PG8_WAIT_L(0); PG8_MMA(0, 1, At, B1); PG8_BAR;
;             PG8_LDA(At, 1, 1); PG8_STAGE(PG8_SA(1, 0), a3, voffA);
	s_add_u32 s34, s24, 0x40000
	s_addc_u32 s35, s25, 0
	s_add_i32 s31, s52, s44
	s_mov_b32 m0, s31
	v_lshl_add_u64 v[142:143], s[34:35], 0, v[132:133]
	global_load_lds_dwordx4 v[142:143], off
	s_add_i32 m0, s31, 0x2000
	v_lshl_add_u64 v[142:143], s[34:35], 0, v[136:137]
	global_load_lds_dwordx4 v[142:143], off
	s_waitcnt vmcnt(6)
	s_barrier
	v_mfma_f32_16x16x32_bf16 v[54:57], v[212:215], v[168:171], v[54:57]
	v_mfma_f32_16x16x32_bf16 v[50:53], v[220:223], v[168:171], v[50:53]
	v_mfma_f32_16x16x32_bf16 v[38:41], v[212:215], v[180:183], v[38:41]
	v_mfma_f32_16x16x32_bf16 v[34:37], v[220:223], v[180:183], v[34:37]
	v_mfma_f32_16x16x32_bf16 v[22:25], v[212:215], v[196:199], v[22:25]
	v_mfma_f32_16x16x32_bf16 v[18:21], v[220:223], v[196:199], v[18:21]
	v_mfma_f32_16x16x32_bf16 v[6:9], v[212:215], v[204:207], v[6:9]
	v_mfma_f32_16x16x32_bf16 v[2:5], v[220:223], v[204:207], v[2:5]
	v_mfma_f32_16x16x32_bf16 v[54:57], v[216:219], v[172:175], v[54:57]
	v_mfma_f32_16x16x32_bf16 v[50:53], v[224:227], v[172:175], v[50:53]
	v_mfma_f32_16x16x32_bf16 v[38:41], v[216:219], v[192:195], v[38:41]
	v_mfma_f32_16x16x32_bf16 v[34:37], v[224:227], v[192:195], v[34:37]
	v_mfma_f32_16x16x32_bf16 v[22:25], v[216:219], v[200:203], v[22:25]
	v_mfma_f32_16x16x32_bf16 v[18:21], v[224:227], v[200:203], v[18:21]
	v_mfma_f32_16x16x32_bf16 v[6:9], v[216:219], v[208:211], v[6:9]
	v_mfma_f32_16x16x32_bf16 v[2:5], v[224:227], v[208:211], v[2:5]
	s_add_i32 s31, 0, 0x18000
	v_add_u32_e32 v159, s31, v152
	s_barrier
	ds_read_b128 v[142:145], v159
	ds_read_b128 v[146:149], v159 offset:1024
	ds_read_b128 v[160:163], v159 offset:2048
	ds_read_b128 v[164:167], v159 offset:3072
	s_add_u32 s26, s26, 0x40000
	s_addc_u32 s27, s27, 0
	s_mov_b32 m0, s47
	v_lshl_add_u64 v[212:213], s[26:27], 0, v[130:131]
	ds_read_b128 v[168:171], v158 offset:32768
	ds_read_b128 v[172:175], v158 offset:33792
	ds_read_b128 v[180:183], v158 offset:34816
	ds_read_b128 v[192:195], v158 offset:35840
	ds_read_b128 v[196:199], v158 offset:36864
	ds_read_b128 v[200:203], v158 offset:37888
	ds_read_b128 v[204:207], v158 offset:38912
	ds_read_b128 v[208:211], v158 offset:39936
	global_load_lds_dwordx4 v[212:213], off
	s_mov_b32 m0, s48
	v_lshl_add_u64 v[212:213], s[26:27], 0, v[134:135]
	global_load_lds_dwordx4 v[212:213], off
	s_waitcnt lgkmcnt(8)
	s_barrier
	s_waitcnt lgkmcnt(0)
	v_mfma_f32_16x16x32_bf16 v[126:129], v[142:145], v[168:171], v[126:129]
	v_mfma_f32_16x16x32_bf16 v[122:125], v[160:163], v[168:171], v[122:125]
	v_mfma_f32_16x16x32_bf16 v[110:113], v[142:145], v[180:183], v[110:113]
	v_mfma_f32_16x16x32_bf16 v[106:109], v[160:163], v[180:183], v[106:109]
	v_mfma_f32_16x16x32_bf16 v[94:97], v[142:145], v[196:199], v[94:97]
	v_mfma_f32_16x16x32_bf16 v[90:93], v[160:163], v[196:199], v[90:93]
	v_mfma_f32_16x16x32_bf16 v[78:81], v[142:145], v[204:207], v[78:81]
	v_mfma_f32_16x16x32_bf16 v[74:77], v[160:163], v[204:207], v[74:77]
	v_mfma_f32_16x16x32_bf16 v[126:129], v[146:149], v[172:175], v[126:129]
	v_mfma_f32_16x16x32_bf16 v[122:125], v[164:167], v[172:175], v[122:125]
	v_mfma_f32_16x16x32_bf16 v[110:113], v[146:149], v[192:195], v[110:113]
	v_mfma_f32_16x16x32_bf16 v[106:109], v[164:167], v[192:195], v[106:109]
	v_mfma_f32_16x16x32_bf16 v[94:97], v[146:149], v[200:203], v[94:97]
	v_mfma_f32_16x16x32_bf16 v[90:93], v[164:167], v[200:203], v[90:93]
	v_mfma_f32_16x16x32_bf16 v[78:81], v[146:149], v[208:211], v[78:81]
	v_mfma_f32_16x16x32_bf16 v[74:77], v[164:167], v[208:211], v[74:77]
	s_barrier
	s_add_i32 s26, 0, 0x1c000
	s_add_i32 s27, s31, s44
	v_add_u32_e32 v159, s26, v152
	v_lshl_add_u64 v[150:151], v[150:151], 0, s[88:89]
	s_mov_b32 m0, s27
	ds_read_b128 v[212:215], v159
	ds_read_b128 v[216:219], v159 offset:1024
	ds_read_b128 v[220:223], v159 offset:2048
	ds_read_b128 v[224:227], v159 offset:3072
	global_load_lds_dwordx4 v[150:151], off
	s_add_i32 m0, s27, 0x2000
	v_lshl_add_u64 v[150:151], v[176:177], 0, s[88:89]
	global_load_lds_dwordx4 v[150:151], off
	s_barrier
; #define PG8_STAGE(bufoff, gbase, voff) do { _Pragma("unroll") for (int _i = 0; _i < 2; ++_i) \
;         __builtin_amdgcn_global_load_lds((const unsigned*)((const char*)(gbase) + (voff)[_i]), (LAS unsigned*)(lds + (bufoff) + ldsw + _i * 8192), 16, 0, 0); } while (0)
; #define PG8_MMA(ai, bj, At, Bt) do { __builtin_amdgcn_s_setprio(1); _Pragma("unroll") for (int m = 0; m < 4; ++m) _Pragma("unroll") for (int n = 0; n < 2; ++n) _Pragma("unroll") for (int k = 0; k < 2; ++k) \
;         acc[ai][bj][m][n] = __builtin_amdgcn_mfma_f32_16x16x32_bf16(Bt[n][k], At[m][k], acc[ai][bj][m][n], 0, 0, 0); __builtin_amdgcn_s_setprio(0); } while (0)
; #define PG8_WAIT_V(n) asm volatile("s_waitcnt vmcnt(" #n ")" ::: "memory")
; #define PG8_WAIT_L(n) asm volatile("s_waitcnt lgkmcnt(" #n ")" ::: "memory")
; #define PG8_BAR __builtin_amdgcn_s_barrier()
; #define PG8_SCHED __builtin_amdgcn_sched_barrier(0)
; __device__ __forceinline__ unsigned xb_ld(unsigned* p)              { return __hip_atomic_load(p, __ATOMIC_RELAXED, __HIP_MEMORY_SCOPE_AGENT); }
; #define XB_SPIN(cond, bar) do { unsigned _sp = 0; while (cond) { __builtin_amdgcn_s_sleep(1); \
;     if ((++_sp & 255u) == 0u) { if (xb_ld(&(bar)[XB_TMO])) break; if (_sp > XB_SPIN_CAP) { atomicAdd(&(bar)[XB_TMO], 1u); break; } } } } while (0)
; template <class Epi, class Sched>
; __device__ __forceinline__ void gemm_phase(const int wv, LAS unsigned char* lds, const Gemm g, const Sched& S, const Epi& E) {
;     ...
;             PG8_BAR; PG8_WAIT_L(0); PG8_MMA(1, 0, At, B0); PG8_BAR; PG8_SCHED;
;             PG8_STAGE(PG8_SB(1, 1), b3 + hstepB, voffB);
;             PG8_WAIT_V(6); PG8_BAR; PG8_MMA(1, 1, At, B1); PG8_BAR;
;         }
;         E(acc, cur, wr, wc, fr, fq); S.done(cur);
; __device__ __forceinline__ void xcd_barrier(const int wv, const XcdBarrier& b) {
;     ...
;             XB_SPIN(xb_ld(&bar[XB_XGEN(b.x)]) == gen, bar);
;             __builtin_amdgcn_fence(__ATOMIC_ACQUIRE, "agent");
	s_waitcnt lgkmcnt(0)
	v_mfma_f32_16x16x32_bf16 v[118:121], v[212:215], v[168:171], v[118:121]
	v_mfma_f32_16x16x32_bf16 v[114:117], v[220:223], v[168:171], v[114:117]
	v_mfma_f32_16x16x32_bf16 v[102:105], v[212:215], v[180:183], v[102:105]
	v_mfma_f32_16x16x32_bf16 v[98:101], v[220:223], v[180:183], v[98:101]
	v_mfma_f32_16x16x32_bf16 v[86:89], v[212:215], v[196:199], v[86:89]
	v_mfma_f32_16x16x32_bf16 v[82:85], v[220:223], v[196:199], v[82:85]
	v_mfma_f32_16x16x32_bf16 v[70:73], v[212:215], v[204:207], v[70:73]
	v_mfma_f32_16x16x32_bf16 v[66:69], v[220:223], v[204:207], v[66:69]
	v_mfma_f32_16x16x32_bf16 v[118:121], v[216:219], v[172:175], v[118:121]
	v_mfma_f32_16x16x32_bf16 v[114:117], v[224:227], v[172:175], v[114:117]
	v_mfma_f32_16x16x32_bf16 v[102:105], v[216:219], v[192:195], v[102:105]
	v_mfma_f32_16x16x32_bf16 v[98:101], v[224:227], v[192:195], v[98:101]
	v_mfma_f32_16x16x32_bf16 v[86:89], v[216:219], v[200:203], v[86:89]
	v_mfma_f32_16x16x32_bf16 v[82:85], v[224:227], v[200:203], v[82:85]
	v_mfma_f32_16x16x32_bf16 v[70:73], v[216:219], v[208:211], v[70:73]
	v_mfma_f32_16x16x32_bf16 v[66:69], v[224:227], v[208:211], v[66:69]
	s_mov_b32 m0, s49
	v_lshl_add_u64 v[150:151], v[228:229], 0, s[88:89]
	s_barrier
	ds_read_b128 v[168:171], v158 offset:49152
	ds_read_b128 v[172:175], v158 offset:50176
	ds_read_b128 v[180:183], v158 offset:51200
	ds_read_b128 v[192:195], v158 offset:52224
	ds_read_b128 v[196:199], v158 offset:53248
	ds_read_b128 v[200:203], v158 offset:54272
	ds_read_b128 v[204:207], v158 offset:55296
	ds_read_b128 v[208:211], v158 offset:56320
	global_load_lds_dwordx4 v[150:151], off
	s_mov_b32 m0, s50
	v_lshl_add_u64 v[150:151], v[230:231], 0, s[88:89]
	global_load_lds_dwordx4 v[150:151], off
	s_barrier
	s_waitcnt lgkmcnt(0)
	v_mfma_f32_16x16x32_bf16 v[62:65], v[142:145], v[168:171], v[62:65]
	v_mfma_f32_16x16x32_bf16 v[58:61], v[160:163], v[168:171], v[58:61]
	v_mfma_f32_16x16x32_bf16 v[46:49], v[142:145], v[180:183], v[46:49]
	v_mfma_f32_16x16x32_bf16 v[42:45], v[160:163], v[180:183], v[42:45]
	v_mfma_f32_16x16x32_bf16 v[30:33], v[142:145], v[196:199], v[30:33]
	v_mfma_f32_16x16x32_bf16 v[26:29], v[160:163], v[196:199], v[26:29]
	v_mfma_f32_16x16x32_bf16 v[14:17], v[142:145], v[204:207], v[14:17]
	v_mfma_f32_16x16x32_bf16 v[10:13], v[160:163], v[204:207], v[10:13]
	v_mfma_f32_16x16x32_bf16 v[62:65], v[146:149], v[172:175], v[62:65]
	v_mfma_f32_16x16x32_bf16 v[58:61], v[164:167], v[172:175], v[58:61]
	v_mfma_f32_16x16x32_bf16 v[46:49], v[146:149], v[192:195], v[46:49]
	v_mfma_f32_16x16x32_bf16 v[42:45], v[164:167], v[192:195], v[42:45]
	v_mfma_f32_16x16x32_bf16 v[30:33], v[146:149], v[200:203], v[30:33]
	v_mfma_f32_16x16x32_bf16 v[26:29], v[164:167], v[200:203], v[26:29]
	v_mfma_f32_16x16x32_bf16 v[14:17], v[146:149], v[208:211], v[14:17]
	v_mfma_f32_16x16x32_bf16 v[10:13], v[164:167], v[208:211], v[10:13]
	s_barrier
	s_add_u32 s24, s24, 0x40080
	s_addc_u32 s25, s25, 0
	s_add_i32 s26, s26, s44
	s_mov_b32 m0, s26
	v_lshl_add_u64 v[142:143], s[24:25], 0, v[132:133]
	global_load_lds_dwordx4 v[142:143], off
	s_add_i32 m0, s26, 0x2000
	v_lshl_add_u64 v[142:143], s[24:25], 0, v[136:137]
	global_load_lds_dwordx4 v[142:143], off
	s_waitcnt vmcnt(6)
	s_barrier
	v_mfma_f32_16x16x32_bf16 v[54:57], v[212:215], v[168:171], v[54:57]
	v_mfma_f32_16x16x32_bf16 v[50:53], v[220:223], v[168:171], v[50:53]
	v_mfma_f32_16x16x32_bf16 v[38:41], v[212:215], v[180:183], v[38:41]
	v_mfma_f32_16x16x32_bf16 v[34:37], v[220:223], v[180:183], v[34:37]
	v_mfma_f32_16x16x32_bf16 v[22:25], v[212:215], v[196:199], v[22:25]
	v_mfma_f32_16x16x32_bf16 v[18:21], v[220:223], v[196:199], v[18:21]
	v_mfma_f32_16x16x32_bf16 v[6:9], v[212:215], v[204:207], v[6:9]
	v_mfma_f32_16x16x32_bf16 v[2:5], v[220:223], v[204:207], v[2:5]
	v_mfma_f32_16x16x32_bf16 v[54:57], v[216:219], v[172:175], v[54:57]
	v_mfma_f32_16x16x32_bf16 v[50:53], v[224:227], v[172:175], v[50:53]
	v_mfma_f32_16x16x32_bf16 v[38:41], v[216:219], v[192:195], v[38:41]
	v_mfma_f32_16x16x32_bf16 v[34:37], v[224:227], v[192:195], v[34:37]
	v_mfma_f32_16x16x32_bf16 v[22:25], v[216:219], v[200:203], v[22:25]
	v_mfma_f32_16x16x32_bf16 v[18:21], v[224:227], v[200:203], v[18:21]
	v_mfma_f32_16x16x32_bf16 v[6:9], v[216:219], v[208:211], v[6:9]
	v_mfma_f32_16x16x32_bf16 v[2:5], v[224:227], v[208:211], v[2:5]
	s_add_i32 s30, s30, 2
	s_add_u32 s22, s22, 0x100
	s_addc_u32 s23, s23, 0
	s_add_u32 s28, s28, 0x100
	s_addc_u32 s29, s29, 0
	s_cmp_gt_u32 s30, 13
	s_barrier
	s_cbranch_scc0 .LBB0_147
	s_cmp_lg_u32 s51, 1
	s_cbranch_scc1 .Lipw_skip
	s_cmp_eq_u32 s101, 0
	s_cbranch_scc1 .Lgwip_done
	v_mov_b32_e32 v222, s98
	v_mov_b32_e32 v223, s99

; __device__ __forceinline__ unsigned xb_ld(unsigned* p)              { return __hip_atomic_load(p, __ATOMIC_RELAXED, __HIP_MEMORY_SCOPE_AGENT); }
; #define XB_SPIN(cond, bar) do { unsigned _sp = 0; while (cond) { __builtin_amdgcn_s_sleep(1); \
;     if ((++_sp & 255u) == 0u) { if (xb_ld(&(bar)[XB_TMO])) break; if (_sp > XB_SPIN_CAP) { atomicAdd(&(bar)[XB_TMO], 1u); break; } } } } while (0)
; __device__ __forceinline__ void xcd_barrier(const int wv, const XcdBarrier& b) {
;     ...
;             XB_SPIN(xb_ld(&bar[XB_XGEN(b.x)]) == gen, bar);
;             __builtin_amdgcn_fence(__ATOMIC_ACQUIRE, "agent");
;             asm volatile("s_waitcnt vmcnt(0)" ::: "memory");
;         }
;     }
;     __syncthreads();
.Lgwip_got:
	buffer_inv sc1
	s_waitcnt vmcnt(0)
	s_mov_b32 s101, 0
.Lgwip_done:
	s_barrier

; __device__ __forceinline__ unsigned xb_ld(unsigned* p)              { return __hip_atomic_load(p, __ATOMIC_RELAXED, __HIP_MEMORY_SCOPE_AGENT); }
; #define XB_SPIN(cond, bar) do { unsigned _sp = 0; while (cond) { __builtin_amdgcn_s_sleep(1); \
;     if ((++_sp & 255u) == 0u) { if (xb_ld(&(bar)[XB_TMO])) break; if (_sp > XB_SPIN_CAP) { atomicAdd(&(bar)[XB_TMO], 1u); break; } } } } while (0)
; #define GSYNC() xcd_barrier(wv, xb)
; __device__ __forceinline__ void xcd_barrier(const int wv, const XcdBarrier& b) {
;     ...
;             XB_SPIN(xb_ld(&bar[XB_XGEN(b.x)]) == gen, bar);
;             __builtin_amdgcn_fence(__ATOMIC_ACQUIRE, "agent");
; __global__ void __launch_bounds__(512, 2) mega(Params p_unused) {
;     ...
;             pg8::gemm_phase<EpiIn, InProjOrder>(wv, lds, gm, S, E);
;         }
;         GSYNC();
.LBB0_266:
	s_setprio 0
	s_cmp_eq_u32 s101, 0
	s_cbranch_scc1 .Lgwipe_done
	v_mov_b32_e32 v222, s98
	v_mov_b32_e32 v223, s99

; __device__ __forceinline__ unsigned xb_ld(unsigned* p)              { return __hip_atomic_load(p, __ATOMIC_RELAXED, __HIP_MEMORY_SCOPE_AGENT); }
; __device__ __forceinline__ unsigned xb_add(unsigned* p, unsigned v) { return __hip_atomic_fetch_add(p, v, __ATOMIC_RELAXED, __HIP_MEMORY_SCOPE_AGENT); }
; #define XB_SPIN(cond, bar) do { unsigned _sp = 0; while (cond) { __builtin_amdgcn_s_sleep(1); \
;     if ((++_sp & 255u) == 0u) { if (xb_ld(&(bar)[XB_TMO])) break; if (_sp > XB_SPIN_CAP) { atomicAdd(&(bar)[XB_TMO], 1u); break; } } } } while (0)
; __device__ __forceinline__ void xcd_barrier(const int wv, const XcdBarrier& b) {
;     ...
;         if (nloc == 0u) { xcd_barrier_complete(bar, b.x, nloc, nx); b.st[0] = nloc; b.st[1] = nx; }
;         const unsigned old = xb_add(&bar[XB_XSUB(b.x)], 1u);
;         const unsigned gen = old / nloc;
;         if (old + 1u == (gen + 1u) * nloc) {
;             __builtin_amdgcn_fence(__ATOMIC_RELEASE, "agent");
;             asm volatile("s_waitcnt vmcnt(0)" ::: "memory");
;             const unsigned og = xb_add(&bar[XB_TOP], 1u);
;             const unsigned tg = og / nx;
;             if (og + 1u == (tg + 1u) * nx) xb_add(&bar[XB_TOPGEN], 1u);
;             else XB_SPIN(xb_ld(&bar[XB_TOPGEN]) == tg, bar);
;             __builtin_amdgcn_fence(__ATOMIC_ACQUIRE, "agent");
;             xb_add(&bar[XB_XGEN(b.x)], 1u);
;             asm volatile("s_waitcnt vmcnt(0)" ::: "memory");
;         } else {
;             XB_SPIN(xb_ld(&bar[XB_XGEN(b.x)]) == gen, bar);
;             __builtin_amdgcn_fence(__ATOMIC_ACQUIRE, "agent");
;             asm volatile("s_waitcnt vmcnt(0)" ::: "memory");
;         }
.LBB0_534:
	v_lshl_add_u64 v[2:3], v[178:179], 2, s[2:3]
	v_add_co_u32_e32 v8, vcc, 0x1000, v2
	v_cvt_f32_u32_e32 v1, v6
	s_nop 0
	v_addc_co_u32_e32 v9, vcc, 0, v3, vcc
	flat_atomic_add v5, v[8:9], v184 offset:1024 sc0
	v_rcp_iflag_f32_e32 v1, v1
	v_sub_u32_e32 v7, 0, v6
	v_mul_f32_e32 v1, 0x4f7ffffe, v1
	v_cvt_u32_f32_e32 v1, v1
	v_mul_lo_u32 v7, v7, v1
	v_mul_hi_u32 v7, v1, v7
	v_add_u32_e32 v1, v1, v7
	s_waitcnt vmcnt(0) lgkmcnt(0)
	v_mul_hi_u32 v1, v5, v1
	v_mul_lo_u32 v7, v1, v6
	v_sub_u32_e32 v7, v5, v7
	v_cmp_ge_u32_e32 vcc, v7, v6
	v_add_u32_e32 v8, 1, v1
	v_add_u32_e32 v5, 1, v5
	v_cndmask_b32_e32 v1, v1, v8, vcc
	v_sub_u32_e32 v8, v7, v6
	v_cndmask_b32_e32 v7, v7, v8, vcc
	v_cmp_ge_u32_e32 vcc, v7, v6
	v_add_u32_e32 v7, 1, v1
	s_nop 0
	v_cndmask_b32_e32 v1, v1, v7, vcc
	v_mad_u64_u32 v[6:7], s[4:5], v6, v1, v[6:7]
	v_cmp_ne_u32_e32 vcc, v5, v6
	s_and_saveexec_b64 s[4:5], vcc
	s_xor_b64 s[4:5], exec, s[4:5]
	s_cbranch_execz .LBB0_547
	s_cmp_eq_u32 s79, 3
	s_cbranch_scc1 .Lrcip_full
	v_add_co_u32_e32 v4, vcc, 0x2400, v2
	s_nop 1
	v_addc_co_u32_e32 v5, vcc, 0, v3, vcc
	s_nop 0
	v_readfirstlane_b32 s98, v4
	v_readfirstlane_b32 s99, v5
	v_readfirstlane_b32 s100, v1
	s_mov_b32 s101, 0x40000
	s_branch .LBB0_547
.Lrcip_full:
	v_add_co_u32_e32 v4, vcc, 0x2000, v2
	s_nop 1
	v_addc_co_u32_e32 v5, vcc, 0, v3, vcc
	flat_load_dword v4, v[4:5] offset:1024 sc1
	s_waitcnt vmcnt(0) lgkmcnt(0)
	v_cmp_eq_u32_e32 vcc, v4, v1
	s_and_saveexec_b64 s[6:7], vcc
	s_cbranch_execz .LBB0_546
	s_mov_b64 s[8:9], 0x2400
	v_lshl_add_u64 v[2:3], v[2:3], 0, s[8:9]
	s_mov_b32 s22, 1
	s_mov_b64 s[8:9], 0
	s_branch .LBB0_538
